# adds: LN1 slab loads batched; HGRN full-pass Qt.S0 / Qt.Kt^T segment as one stream with LDS reads in flight; sample-item decay scan and pair-dot LDS reads batched
# speedup vs baseline: 1.0167x; 1.0008x over previous
.LBB0_313:
	s_movk_i32 s10, 0x80
	v_cmp_gt_i32_e32 vcc, s10, v47
	s_and_saveexec_b64 s[36:37], vcc
	s_cbranch_execz .LBB0_315
	ds_read2st64_b32 v[48:49], v46 offset0:51 offset1:53
	ds_read2st64_b32 v[50:51], v46 offset0:55 offset1:57
	ds_read2st64_b32 v[52:53], v46 offset0:59 offset1:61
	ds_read2st64_b32 v[54:55], v46 offset0:63 offset1:65
	ds_read_b32 v56, v46 offset:17152
	ds_read_b32 v57, v46 offset:17664
	ds_read_b32 v58, v46 offset:18176
	ds_read_b32 v59, v46 offset:18688
	ds_read_b32 v60, v46 offset:19200
	ds_read_b32 v61, v46 offset:19712
	ds_read_b32 v62, v46 offset:20224
	ds_read_b32 v63, v46 offset:20736
	v_mad_u64_u32 v[64:65], s[10:11], v47, 28, v[46:47]
	s_waitcnt lgkmcnt(8)
	v_sub_f32_e32 v98, 1.0, v48
	v_sub_f32_e32 v99, 1.0, v49
	v_sub_f32_e32 v100, 1.0, v50
	v_sub_f32_e32 v101, 1.0, v51
	v_sub_f32_e32 v102, 1.0, v52
	v_sub_f32_e32 v103, 1.0, v53
	v_sub_f32_e32 v104, 1.0, v54
	v_sub_f32_e32 v105, 1.0, v55
	v_mul_f32_e32 v49, v48, v49
	v_mul_f32_e32 v50, v49, v50
	v_mul_f32_e32 v51, v50, v51
	v_mul_f32_e32 v52, v51, v52
	v_mul_f32_e32 v53, v52, v53
	v_mul_f32_e32 v54, v53, v54
	v_mul_f32_e32 v55, v54, v55
	v_rcp_f32_e32 v106, v48
	v_rcp_f32_e32 v107, v49
	v_rcp_f32_e32 v108, v50
	v_rcp_f32_e32 v109, v51
	v_mul_f32_e32 v98, v98, v106
	v_mul_f32_e32 v99, v99, v107
	v_mul_f32_e32 v100, v100, v108
	v_mul_f32_e32 v101, v101, v109
	v_rcp_f32_e32 v106, v52
	v_rcp_f32_e32 v107, v53
	v_rcp_f32_e32 v108, v54
	v_rcp_f32_e32 v109, v55
	v_mul_f32_e32 v102, v102, v106
	v_mul_f32_e32 v103, v103, v107
	v_mul_f32_e32 v104, v104, v108
	v_mul_f32_e32 v105, v105, v109
	s_waitcnt lgkmcnt(0)
	v_mul_f32_e32 v56, v48, v56
	v_mul_f32_e32 v57, v49, v57
	v_mul_f32_e32 v58, v50, v58
	v_mul_f32_e32 v59, v51, v59
	v_mul_f32_e32 v60, v52, v60
	v_mul_f32_e32 v61, v53, v61
	v_mul_f32_e32 v62, v54, v62
	v_mul_f32_e32 v63, v55, v63
	ds_write_b128 v64, v[56:59]
	ds_write_b128 v64, v[60:63] offset:16
	ds_write_b128 v64, v[98:101] offset:4096
	ds_write_b128 v64, v[102:105] offset:4112
	ds_write_b32 v46, v55 offset:12288
.LBB0_315:
	s_or_b64 exec, exec, s[36:37]
	v_ashrrev_i32_e32 v46, 3, v47
	v_and_b32_e32 v54, 7, v47
	v_and_b32_e32 v48, 7, v46
	v_lshlrev_b32_e32 v49, 2, v134
	v_lshlrev_b32_e32 v52, 2, v48
	v_lshlrev_b32_e32 v53, 5, v54
	v_add3_u32 v49, 0, v49, v53
	v_add3_u32 v55, 0, v52, v53
	s_waitcnt lgkmcnt(0)
	s_barrier
	ds_read2st64_b32 v[138:139], v49 offset1:1
	ds_read2st64_b32 v[140:141], v55 offset0:16 offset1:17
	ds_read2st64_b32 v[142:143], v49 offset0:2 offset1:3
	ds_read2st64_b32 v[144:145], v55 offset0:18 offset1:19
	ds_read2st64_b32 v[148:149], v49 offset0:4 offset1:5
	ds_read2st64_b32 v[150:151], v55 offset0:20 offset1:21
	ds_read2st64_b32 v[152:153], v49 offset0:6 offset1:7
	ds_read2st64_b32 v[158:159], v55 offset0:22 offset1:23
	ds_read2st64_b32 v[160:161], v49 offset0:8 offset1:9
	ds_read2st64_b32 v[162:163], v55 offset0:24 offset1:25
	ds_read2st64_b32 v[164:165], v49 offset0:10 offset1:11
	ds_read2st64_b32 v[166:167], v55 offset0:26 offset1:27
	ds_read2st64_b32 v[98:99], v49 offset0:12 offset1:13
	ds_read2st64_b32 v[100:101], v55 offset0:28 offset1:29
	ds_read2st64_b32 v[102:103], v49 offset0:14 offset1:15
	ds_read2st64_b32 v[104:105], v55 offset0:30 offset1:31
	s_waitcnt lgkmcnt(14)
	v_fma_f32 v56, v138, v140, 0
	v_fmac_f32_e32 v56, v139, v141
	s_waitcnt lgkmcnt(12)
	v_fmac_f32_e32 v56, v142, v144
	v_fmac_f32_e32 v56, v143, v145
	s_waitcnt lgkmcnt(10)
	v_fmac_f32_e32 v56, v148, v150
	v_fmac_f32_e32 v56, v149, v151
	s_waitcnt lgkmcnt(8)
	v_fmac_f32_e32 v56, v152, v158
	v_fmac_f32_e32 v56, v153, v159
	s_waitcnt lgkmcnt(6)
	v_fmac_f32_e32 v56, v160, v162
	v_fmac_f32_e32 v56, v161, v163
	s_waitcnt lgkmcnt(4)
	v_fmac_f32_e32 v56, v164, v166
	v_fmac_f32_e32 v56, v165, v167
	s_waitcnt lgkmcnt(2)
	v_fmac_f32_e32 v56, v98, v100
	v_fmac_f32_e32 v56, v99, v101
	s_waitcnt lgkmcnt(0)
	v_fmac_f32_e32 v56, v102, v104
	v_fmac_f32_e32 v56, v103, v105
	v_xor_b32_e32 v49, 1, v175
	v_and_b32_e32 v50, 64, v175
	v_add_u32_e32 v146, 64, v50
	v_cmp_lt_i32_e32 vcc, v49, v146
	v_xor_b32_e32 v50, 2, v175
	s_nop 0
	v_cndmask_b32_e32 v49, v175, v49, vcc
	v_lshlrev_b32_e32 v182, 2, v49
	ds_bpermute_b32 v49, v182, v56
	v_cmp_lt_i32_e32 vcc, v50, v146
	s_waitcnt lgkmcnt(0)
	v_add_f32_e32 v49, v56, v49
	v_cndmask_b32_e32 v50, v175, v50, vcc
	v_lshlrev_b32_e32 v183, 2, v50
	ds_bpermute_b32 v50, v183, v49
	s_waitcnt lgkmcnt(0)
	v_add_f32_e32 v49, v49, v50
	v_xor_b32_e32 v50, 4, v175
	v_cmp_lt_i32_e32 vcc, v50, v146
	s_nop 1
	v_cndmask_b32_e32 v50, v175, v50, vcc
	v_lshlrev_b32_e32 v184, 2, v50
	ds_bpermute_b32 v50, v184, v49
	v_cmp_eq_u32_e32 vcc, 0, v54
	s_and_saveexec_b64 s[36:37], vcc
	s_cbranch_execz .LBB0_317
	s_waitcnt lgkmcnt(0)
	v_add_f32_e32 v49, v49, v50
	v_cmp_le_i32_e32 vcc, v48, v134
	v_lshl_add_u32 v46, v46, 2, 0
	s_nop 0
	v_cndmask_b32_e32 v48, 0, v49, vcc
	ds_write_b32 v46, v48 offset:12800

.Lhgl_done_b:
	s_add_i32 s93, s92, 15
	s_cmp_gt_i32 s18, s93
	s_cselect_b64 s[92:93], -1, 0
	s_add_i32 s12, s24, 1
	s_cmp_ge_u32 s12, s5
	s_cselect_b64 s[0:1], -1, 0
	s_cmp_lt_u32 s12, s5
	s_cselect_b32 s10, s12, s24
	s_waitcnt lgkmcnt(0)
	s_barrier
	ds_read_b128 v[122:125], v179
	s_and_b64 vcc, exec, s[36:37]
	s_mov_b64 s[10:11], -1
	s_cbranch_vccnz .LBB0_432
	v_lshl_add_u32 v34, s24, 6, v163
	v_cmp_gt_i32_e32 vcc, s18, v34
	v_add_u32_e32 v34, s23, v34
	v_mov_b32_e32 v134, 0
	v_cndmask_b32_e32 v34, v164, v34, vcc
	v_ashrrev_i32_e32 v35, 31, v34
	v_lshlrev_b64 v[152:153], 11, v[34:35]
	v_or_b32_e32 v152, v152, v150
	v_lshl_add_u64 v[34:35], v[152:153], 1, s[14:15]
	global_load_dwordx4 v[118:121], v[34:35], off offset:16 nt
	global_load_dwordx4 v[126:129], v[34:35], off nt
	ds_read_b128 v[50:53], v180
	ds_read_b128 v[46:49], v180 offset:64
	ds_read_b128 v[42:45], v180 offset:128
	ds_read_b128 v[38:41], v180 offset:192
	ds_read_b128 v[130:133], v181
	ds_read_b128 v[134:137], v181 offset:64
	ds_read_b128 v[138:141], v181 offset:128
	ds_read_b128 v[142:145], v181 offset:192
	ds_read_b128 v[244:247], v181 offset:4352
	ds_read_b128 v[248:251], v181 offset:4416
	s_waitcnt lgkmcnt(5)
	v_mfma_f32_16x16x32_bf16 v[34:37], v[50:53], v[130:133], 0
	ds_read_b128 v[130:133], v181 offset:4480
	s_waitcnt lgkmcnt(5)
	v_mfma_f32_16x16x32_bf16 v[34:37], v[46:49], v[134:137], v[34:37]
	ds_read_b128 v[134:137], v181 offset:4544
	s_waitcnt lgkmcnt(5)
	v_mfma_f32_16x16x32_bf16 v[34:37], v[42:45], v[138:141], v[34:37]
	ds_read_b128 v[138:141], v181 offset:8704
	s_waitcnt lgkmcnt(5)
	v_mfma_f32_16x16x32_bf16 v[34:37], v[38:41], v[142:145], v[34:37]
	ds_read_b128 v[142:145], v181 offset:8768
	s_waitcnt lgkmcnt(5)
	v_mfma_f32_16x16x32_bf16 v[54:57], v[50:53], v[244:247], 0
	ds_read_b128 v[244:247], v181 offset:8832
	s_waitcnt lgkmcnt(5)
	v_mfma_f32_16x16x32_bf16 v[54:57], v[46:49], v[248:251], v[54:57]
	ds_read_b128 v[248:251], v181 offset:8896
	s_waitcnt lgkmcnt(5)
	v_mfma_f32_16x16x32_bf16 v[54:57], v[42:45], v[130:133], v[54:57]
	ds_read_b128 v[130:133], v181 offset:13056
	s_waitcnt lgkmcnt(5)
	v_mfma_f32_16x16x32_bf16 v[54:57], v[38:41], v[134:137], v[54:57]
	ds_read_b128 v[134:137], v181 offset:13120
	s_waitcnt lgkmcnt(5)
	v_mfma_f32_16x16x32_bf16 v[58:61], v[50:53], v[138:141], 0
	ds_read_b128 v[138:141], v181 offset:13184
	s_waitcnt lgkmcnt(5)
	v_mfma_f32_16x16x32_bf16 v[58:61], v[46:49], v[142:145], v[58:61]
	ds_read_b128 v[142:145], v181 offset:13248
	s_waitcnt lgkmcnt(5)
	v_mfma_f32_16x16x32_bf16 v[58:61], v[42:45], v[244:247], v[58:61]
	ds_read_b128 v[244:247], v194 offset:17408
	s_waitcnt lgkmcnt(5)
	v_mfma_f32_16x16x32_bf16 v[58:61], v[38:41], v[248:251], v[58:61]
	ds_read_b128 v[248:251], v194 offset:17472
	s_waitcnt lgkmcnt(5)
	v_mfma_f32_16x16x32_bf16 v[62:65], v[50:53], v[130:133], 0
	ds_read_b128 v[130:133], v194 offset:17536
	s_waitcnt lgkmcnt(5)
	v_mfma_f32_16x16x32_bf16 v[62:65], v[46:49], v[134:137], v[62:65]
	ds_read_b128 v[134:137], v194 offset:17600
	s_waitcnt lgkmcnt(5)
	v_mfma_f32_16x16x32_bf16 v[62:65], v[42:45], v[138:141], v[62:65]
	ds_read_b128 v[138:141], v194 offset:21760
	s_waitcnt lgkmcnt(5)
	v_mfma_f32_16x16x32_bf16 v[62:65], v[38:41], v[142:145], v[62:65]
	ds_read_b128 v[142:145], v194 offset:21824
	s_waitcnt lgkmcnt(5)
	v_mfma_f32_16x16x32_bf16 v[244:247], v[50:53], v[244:247], 0
	s_waitcnt lgkmcnt(4)
	v_mfma_f32_16x16x32_bf16 v[244:247], v[46:49], v[248:251], v[244:247]
	ds_read_b128 v[248:251], v194 offset:21888
	s_waitcnt lgkmcnt(4)
	v_mfma_f32_16x16x32_bf16 v[244:247], v[42:45], v[130:133], v[244:247]
	ds_read_b128 v[130:133], v194 offset:21952
	s_waitcnt lgkmcnt(4)
	v_mfma_f32_16x16x32_bf16 v[244:247], v[38:41], v[134:137], v[244:247]
	s_waitcnt lgkmcnt(3)
	v_mfma_f32_16x16x32_bf16 v[138:141], v[50:53], v[138:141], 0
	s_waitcnt lgkmcnt(2)
	v_mfma_f32_16x16x32_bf16 v[138:141], v[46:49], v[142:145], v[138:141]
	s_waitcnt lgkmcnt(1)
	v_mfma_f32_16x16x32_bf16 v[138:141], v[42:45], v[248:251], v[138:141]
	s_waitcnt lgkmcnt(0)
	v_mfma_f32_16x16x32_bf16 v[138:141], v[38:41], v[130:133], v[138:141]
	s_nop 3
	v_cndmask_b32_e64 v38, v244, 0, s[46:47]
	v_bfe_u32 v39, v38, 16, 1
	v_add3_u32 v38, v38, v39, s25
	ds_write_b16_d16_hi v182, v38
	v_cndmask_b32_e64 v38, v245, 0, s[48:49]
	v_bfe_u32 v39, v38, 16, 1
	v_add3_u32 v38, v38, v39, s25
	ds_write_b16_d16_hi v182, v38 offset:144
	v_cndmask_b32_e64 v38, v246, 0, s[50:51]
	v_bfe_u32 v39, v38, 16, 1
	v_add3_u32 v38, v38, v39, s25
	ds_write_b16_d16_hi v182, v38 offset:288
	v_cndmask_b32_e64 v38, v247, 0, s[52:53]
	v_bfe_u32 v39, v38, 16, 1
	v_add3_u32 v38, v38, v39, s25
	ds_write_b16_d16_hi v182, v38 offset:432
	v_cndmask_b32_e64 v38, v138, 0, s[54:55]
	v_bfe_u32 v39, v38, 16, 1
	v_add3_u32 v38, v38, v39, s25
	ds_write_b16_d16_hi v183, v38
	v_cndmask_b32_e64 v38, v139, 0, s[56:57]
	v_bfe_u32 v39, v38, 16, 1
	v_add3_u32 v38, v38, v39, s25
	ds_write_b16_d16_hi v183, v38 offset:144
	v_cndmask_b32_e64 v38, v140, 0, s[58:59]
	v_bfe_u32 v39, v38, 16, 1
	v_add3_u32 v38, v38, v39, s25
	ds_write_b16_d16_hi v183, v38 offset:288
	v_cndmask_b32_e64 v38, v141, 0, s[60:61]
	v_bfe_u32 v39, v38, 16, 1
	v_add3_u32 v38, v38, v39, s25
	ds_write_b16_d16_hi v183, v38 offset:432
	s_waitcnt lgkmcnt(0)
	s_barrier
	v_add_u32_e32 v243, v167, v165
	v_add_u32_e32 v252, v166, v176
	s_mov_b64 s[10:11], 0
	ds_read_b128 v[244:247], v184
	ds_read_b128 v[130:133], v185 offset:53248
	ds_read_b128 v[134:137], v185 offset:55552
	ds_read_b128 v[138:141], v185 offset:57856
	ds_read_b128 v[142:145], v185 offset:60160
	ds_read_b128 v[248:251], v184 offset:64
	ds_read_b128 v[38:41], v185 offset:53312
	ds_read_b128 v[42:45], v185 offset:55616
	ds_read_b128 v[46:49], v185 offset:57920
	ds_read_b128 v[50:53], v185 offset:60224
	s_waitcnt lgkmcnt(8)
	v_mfma_f32_16x16x32_bf16 v[34:37], v[244:247], v[130:133], v[34:37]
	s_waitcnt lgkmcnt(7)
	v_mfma_f32_16x16x32_bf16 v[54:57], v[244:247], v[134:137], v[54:57]
	s_waitcnt lgkmcnt(6)
	v_mfma_f32_16x16x32_bf16 v[58:61], v[244:247], v[138:141], v[58:61]
	s_waitcnt lgkmcnt(5)
	v_mfma_f32_16x16x32_bf16 v[62:65], v[244:247], v[142:145], v[62:65]
	ds_read_b128 v[244:247], v243 offset:34816
	s_waitcnt lgkmcnt(4)
	v_mfma_f32_16x16x32_bf16 v[130:133], v[248:251], v[38:41], v[34:37]
	ds_read_b128 v[38:41], v252 offset:53248
	s_waitcnt lgkmcnt(4)
	v_mfma_f32_16x16x32_bf16 v[134:137], v[248:251], v[42:45], v[54:57]
	ds_read_b128 v[42:45], v252 offset:55552
	s_waitcnt lgkmcnt(4)
	v_mfma_f32_16x16x32_bf16 v[138:141], v[248:251], v[46:49], v[58:61]
	ds_read_b128 v[46:49], v252 offset:57856
	s_waitcnt lgkmcnt(4)
	v_mfma_f32_16x16x32_bf16 v[142:145], v[248:251], v[50:53], v[62:65]
	ds_read_b128 v[50:53], v252 offset:60160
	ds_read_b128 v[248:251], v243 offset:34880
	ds_read_b128 v[34:37], v252 offset:62464
	ds_read_b128 v[54:57], v252 offset:64768
	ds_read_b128 v[58:61], v186 offset:64768
	ds_read_b128 v[62:65], v187 offset:64768
	s_waitcnt lgkmcnt(8)
	v_mfma_f32_16x16x32_bf16 v[2:5], v[244:247], v[38:41], v[2:5]
	ds_read_b128 v[38:41], v252 offset:53312
	s_waitcnt lgkmcnt(8)
	v_mfma_f32_16x16x32_bf16 v[6:9], v[244:247], v[42:45], v[6:9]
	ds_read_b128 v[42:45], v252 offset:55616
	s_waitcnt lgkmcnt(8)
	v_mfma_f32_16x16x32_bf16 v[10:13], v[244:247], v[46:49], v[10:13]
	ds_read_b128 v[46:49], v252 offset:57920
	s_waitcnt lgkmcnt(8)
	v_mfma_f32_16x16x32_bf16 v[14:17], v[244:247], v[50:53], v[14:17]
	ds_read_b128 v[50:53], v252 offset:60224
	s_waitcnt lgkmcnt(7)
	v_mfma_f32_16x16x32_bf16 v[18:21], v[244:247], v[34:37], v[18:21]
	ds_read_b128 v[34:37], v252 offset:62528
	s_waitcnt lgkmcnt(7)
	v_mfma_f32_16x16x32_bf16 v[22:25], v[244:247], v[54:57], v[22:25]
	ds_read_b128 v[54:57], v252 offset:64832
	s_waitcnt lgkmcnt(7)
	v_mfma_f32_16x16x32_bf16 v[26:29], v[244:247], v[58:61], v[26:29]
	ds_read_b128 v[58:61], v186 offset:64832
	s_waitcnt lgkmcnt(7)
	v_mfma_f32_16x16x32_bf16 v[30:33], v[244:247], v[62:65], v[30:33]
	ds_read_b128 v[62:65], v187 offset:64832
	s_waitcnt lgkmcnt(7)
	v_mfma_f32_16x16x32_bf16 v[2:5], v[248:251], v[38:41], v[2:5]
	s_waitcnt lgkmcnt(6)
	v_mfma_f32_16x16x32_bf16 v[6:9], v[248:251], v[42:45], v[6:9]
	s_waitcnt lgkmcnt(5)
	v_mfma_f32_16x16x32_bf16 v[10:13], v[248:251], v[46:49], v[10:13]
	s_waitcnt lgkmcnt(4)
	v_mfma_f32_16x16x32_bf16 v[14:17], v[248:251], v[50:53], v[14:17]
	s_waitcnt lgkmcnt(3)
	v_mfma_f32_16x16x32_bf16 v[18:21], v[248:251], v[34:37], v[18:21]
	s_waitcnt lgkmcnt(2)
	v_mfma_f32_16x16x32_bf16 v[22:25], v[248:251], v[54:57], v[22:25]
	s_waitcnt lgkmcnt(1)
	v_mfma_f32_16x16x32_bf16 v[26:29], v[248:251], v[58:61], v[26:29]
	s_waitcnt lgkmcnt(0)
	v_mfma_f32_16x16x32_bf16 v[30:33], v[248:251], v[62:65], v[30:33]
	v_pk_mul_f32 v[34:35], v[122:123], v[2:3]
	v_mul_f32_e64 v36, v124, v4
	v_mul_f32_e64 v37, v125, v5
	v_pk_mul_f32 v[38:39], v[122:123], v[6:7]
	v_pk_mul_f32 v[40:41], v[124:125], v[8:9]
	v_pk_mul_f32 v[42:43], v[122:123], v[10:11]
	v_pk_mul_f32 v[44:45], v[124:125], v[12:13]
	v_pk_mul_f32 v[46:47], v[122:123], v[14:15]
	v_pk_mul_f32 v[48:49], v[124:125], v[16:17]
	v_pk_mul_f32 v[50:51], v[122:123], v[18:19]
	v_pk_mul_f32 v[52:53], v[124:125], v[20:21]
	v_pk_mul_f32 v[54:55], v[122:123], v[22:23]
	v_pk_mul_f32 v[56:57], v[124:125], v[24:25]
	v_pk_mul_f32 v[58:59], v[122:123], v[26:27]
	v_pk_mul_f32 v[60:61], v[124:125], v[28:29]
	v_pk_mul_f32 v[62:63], v[122:123], v[30:31]
	v_pk_mul_f32 v[64:65], v[124:125], v[32:33]
	v_cvt_pk_bf16_f32 v244, v34, v35
	v_cvt_pk_bf16_f32 v245, v36, v37
	ds_write_b64 v188, v[244:245]
	v_cvt_pk_bf16_f32 v246, v38, v39
	v_cvt_pk_bf16_f32 v247, v40, v41
	ds_write_b64 v188, v[246:247] offset:4352
	v_cvt_pk_bf16_f32 v248, v42, v43
	v_cvt_pk_bf16_f32 v249, v44, v45
	ds_write_b64 v188, v[248:249] offset:8704
	v_cvt_pk_bf16_f32 v250, v46, v47
	v_cvt_pk_bf16_f32 v251, v48, v49
	ds_write_b64 v188, v[250:251] offset:13056
	v_cvt_pk_bf16_f32 v244, v50, v51
	v_cvt_pk_bf16_f32 v245, v52, v53
	ds_write_b64 v188, v[244:245] offset:17408
	v_cvt_pk_bf16_f32 v246, v54, v55
	v_cvt_pk_bf16_f32 v247, v56, v57
	ds_write_b64 v188, v[246:247] offset:21760
	v_cvt_pk_bf16_f32 v248, v58, v59
	v_cvt_pk_bf16_f32 v249, v60, v61
	ds_write_b64 v188, v[248:249] offset:26112
	v_cvt_pk_bf16_f32 v250, v62, v63
	v_cvt_pk_bf16_f32 v251, v64, v65
	ds_write_b64 v188, v[250:251] offset:30464
	ds_write2_b32 v189, v130, v134 offset1:16
	ds_write2_b32 v189, v131, v135 offset0:132 offset1:148
	v_add_u32_e32 v130, 0x400, v189
	ds_write2_b32 v130, v132, v136 offset0:8 offset1:24
	ds_write2_b32 v130, v133, v137 offset0:140 offset1:156
	ds_write2_b32 v189, v138, v142 offset0:32 offset1:48
	ds_write2_b32 v189, v139, v143 offset0:164 offset1:180
	ds_write2_b32 v130, v140, v144 offset0:40 offset1:56
	ds_write2_b32 v130, v141, v145 offset0:172 offset1:188
	s_waitcnt lgkmcnt(0)
	s_barrier
	ds_read_b128 v[130:133], v190
	ds_read_b128 v[134:137], v190 offset:16
	ds_read_b128 v[138:141], v190 offset:32
	ds_read_b128 v[142:145], v190 offset:48
	s_waitcnt lgkmcnt(3)
	v_pk_mul_f32 v[244:245], v[132:133], v[132:133]
	v_pk_mul_f32 v[246:247], v[130:131], v[130:131]
	s_waitcnt lgkmcnt(0)
	v_mul_f32_e32 v243, v142, v142
	v_pk_mov_b32 v[248:249], v[246:247], v[244:245] op_sel:[1,0]
	v_mov_b32_e32 v247, v245
	v_pk_add_f32 v[244:245], v[248:249], v[246:247]
	v_pk_mul_f32 v[246:247], v[136:137], v[136:137]
	v_pk_mul_f32 v[248:249], v[134:135], v[134:135]
	v_pk_add_f32 v[244:245], v[244:245], v[244:245] op_sel:[0,1] op_sel_hi:[1,0]
	v_pk_mov_b32 v[250:251], v[248:249], v[246:247] op_sel:[1,0]
	v_mov_b32_e32 v249, v247
	v_pk_add_f32 v[246:247], v[250:251], v[248:249]
	v_mul_f32_e32 v248, v143, v143
	v_pk_add_f32 v[246:247], v[246:247], v[246:247] op_sel:[0,1] op_sel_hi:[1,0]
	v_mov_b32_e32 v245, v243
	v_mov_b32_e32 v247, v248
	v_pk_add_f32 v[244:245], v[244:245], v[246:247]
	v_mul_f32_e32 v246, v139, v139
	v_mul_f32_e32 v249, v144, v144
	v_pk_fma_f32 v[246:247], v[138:139], v[138:139], v[246:247] op_sel_hi:[1,1,0]
	v_mul_f32_e32 v248, v141, v141
	v_mul_f32_e32 v250, v145, v145
	v_mov_b32_e32 v247, v249
	v_pk_fma_f32 v[248:249], v[140:141], v[140:141], v[248:249] op_sel_hi:[1,1,0]
	s_nop 0
	v_mov_b32_e32 v249, v250
	v_pk_add_f32 v[246:247], v[246:247], v[248:249]
	s_nop 0
	v_pk_add_f32 v[244:245], v[244:245], v[246:247]
	s_nop 0
	v_add_f32_e32 v243, v244, v245
	v_and_b32_e32 v245, 64, v175
	v_xor_b32_e32 v244, 1, v175
	v_add_u32_e32 v245, 64, v245
	v_cmp_lt_i32_e32 vcc, v244, v245
	s_nop 1
	v_cndmask_b32_e32 v244, v175, v244, vcc
	v_lshlrev_b32_e32 v244, 2, v244
	ds_bpermute_b32 v244, v244, v243
	s_waitcnt lgkmcnt(0)
	v_add_f32_e32 v243, v243, v244
	v_xor_b32_e32 v244, 2, v175
	v_cmp_lt_i32_e32 vcc, v244, v245
	s_nop 1
	v_cndmask_b32_e32 v244, v175, v244, vcc
	v_lshlrev_b32_e32 v244, 2, v244
	ds_bpermute_b32 v244, v244, v243
	s_waitcnt lgkmcnt(0)
	v_add_f32_e32 v243, v243, v244
	v_xor_b32_e32 v244, 4, v175
	v_cmp_lt_i32_e32 vcc, v244, v245
	s_nop 1
	v_cndmask_b32_e32 v244, v175, v244, vcc
	v_lshlrev_b32_e32 v244, 2, v244
	ds_bpermute_b32 v244, v244, v243
	s_waitcnt lgkmcnt(0)
	v_add_f32_e32 v243, v243, v244
	v_fmamk_f32 v243, v243, 0x3c000000, v1
	v_cmp_gt_f32_e32 vcc, s33, v243
	v_mul_f32_e32 v244, 0x4b800000, v243
	s_nop 0
	v_cndmask_b32_e32 v243, v243, v244, vcc
	v_rsq_f32_e32 v243, v243
	s_nop 0
	v_mul_f32_e32 v244, 0x45800000, v243
	v_cndmask_b32_e32 v243, v243, v244, vcc
	v_mul_f32_e32 v131, v131, v243
	s_waitcnt vmcnt(0)
	v_lshlrev_b32_e32 v244, 16, v126
	v_mul_f32_e32 v131, v111, v131
	v_and_b32_e32 v126, 0xffff0000, v126
	v_mul_f32_e32 v126, v131, v126
	v_mul_f32_e32 v131, v132, v243
	v_mul_f32_e32 v130, v130, v243
	v_mul_f32_e32 v131, v112, v131
	v_lshlrev_b32_e32 v132, 16, v127
	v_mul_f32_e32 v130, v110, v130
	v_mul_f32_e32 v131, v131, v132
	v_mul_f32_e32 v132, v133, v243
	v_mul_f32_e32 v130, v130, v244
	v_mul_f32_e32 v132, v113, v132
	v_and_b32_e32 v127, 0xffff0000, v127
	v_mul_f32_e32 v127, v132, v127
	v_cvt_pk_bf16_f32 v126, v130, v126
	v_mul_f32_e32 v130, v134, v243
	v_cvt_pk_bf16_f32 v127, v131, v127
	v_mul_f32_e32 v130, v106, v130
	v_lshlrev_b32_e32 v131, 16, v128
	v_mul_f32_e32 v130, v130, v131
	v_mul_f32_e32 v131, v135, v243
	v_mul_f32_e32 v131, v107, v131
	v_and_b32_e32 v128, 0xffff0000, v128
	v_mul_f32_e32 v128, v131, v128
	v_mul_f32_e32 v131, v136, v243
	v_mul_f32_e32 v131, v108, v131
	v_lshlrev_b32_e32 v132, 16, v129
	v_mul_f32_e32 v131, v131, v132
	v_mul_f32_e32 v132, v137, v243
	v_mul_f32_e32 v132, v109, v132
	v_and_b32_e32 v129, 0xffff0000, v129
	v_mul_f32_e32 v129, v132, v129
	v_cvt_pk_bf16_f32 v128, v130, v128
	v_mul_f32_e32 v130, v138, v243
	v_cvt_pk_bf16_f32 v129, v131, v129
	v_mul_f32_e32 v130, v102, v130
	v_lshlrev_b32_e32 v131, 16, v118
	v_mul_f32_e32 v130, v130, v131
	v_mul_f32_e32 v131, v139, v243
	v_mul_f32_e32 v131, v103, v131
	v_and_b32_e32 v118, 0xffff0000, v118
	v_mul_f32_e32 v118, v131, v118
	v_mul_f32_e32 v131, v140, v243
	v_mul_f32_e32 v131, v104, v131
	v_lshlrev_b32_e32 v132, 16, v119
	v_mul_f32_e32 v131, v131, v132
	v_mul_f32_e32 v132, v141, v243
	v_mul_f32_e32 v132, v105, v132
	v_and_b32_e32 v119, 0xffff0000, v119
	v_mul_f32_e32 v119, v132, v119
	v_cvt_pk_bf16_f32 v118, v130, v118
	v_mul_f32_e32 v130, v142, v243
	v_cvt_pk_bf16_f32 v119, v131, v119
	v_mul_f32_e32 v130, v98, v130
	v_lshlrev_b32_e32 v131, 16, v120
	v_mul_f32_e32 v130, v130, v131
	v_mul_f32_e32 v131, v143, v243
	v_mul_f32_e32 v131, v99, v131
	v_and_b32_e32 v120, 0xffff0000, v120
	v_mul_f32_e32 v120, v131, v120
	v_mul_f32_e32 v131, v144, v243
	v_mul_f32_e32 v131, v100, v131
	v_lshlrev_b32_e32 v132, 16, v121
	v_mul_f32_e32 v131, v131, v132
	v_mul_f32_e32 v132, v145, v243
	v_mul_f32_e32 v132, v101, v132
	v_and_b32_e32 v121, 0xffff0000, v121
	v_mul_f32_e32 v121, v132, v121
	v_cvt_pk_bf16_f32 v120, v130, v120
	v_cvt_pk_bf16_f32 v121, v131, v121
	v_lshl_add_u64 v[130:131], v[152:153], 1, s[30:31]
	global_store_dwordx4 v[130:131], v[126:129], off
	global_store_dwordx4 v[130:131], v[118:121], off offset:16

.LBB0_709:
	s_movk_i32 s10, 0x1fff
	v_cmp_lt_u32_e32 vcc, s10, v120
	s_and_saveexec_b64 s[10:11], vcc
	s_xor_b64 s[10:11], exec, s[10:11]
	s_cbranch_execz .LBB0_711
	v_add_u32_e32 v98, 0xffffe000, v120
	v_mov_b32_e32 v99, v103
	v_lshlrev_b64 v[98:99], 13, v[98:99]
	v_lshl_add_u64 v[98:99], v[122:123], 0, v[98:99]
	v_add_co_u32_e32 v186, vcc, 0x1000, v98
	s_nop 1
	v_addc_co_u32_e32 v187, vcc, 0, v99, vcc
	v_add_co_u32_e32 v104, vcc, 0x881000, v98
	s_nop 1
	v_addc_co_u32_e32 v105, vcc, 0, v99, vcc
	v_add_co_u32_e32 v106, vcc, 0x1101000, v98
	s_nop 1
	v_addc_co_u32_e32 v107, vcc, 0, v99, vcc
	v_add_co_u32_e32 v108, vcc, 0x1981000, v98
	s_nop 1
	v_addc_co_u32_e32 v109, vcc, 0, v99, vcc
	global_load_dwordx4 v[188:191], v[186:187], off offset:-4096 nt
	global_load_dwordx4 v[192:195], v[186:187], off offset:-3072 nt
	global_load_dwordx4 v[196:199], v[186:187], off offset:-2048 nt
	global_load_dwordx4 v[200:203], v[186:187], off offset:-1024 nt
	global_load_dwordx4 v[204:207], v[186:187], off nt
	global_load_dwordx4 v[208:211], v[186:187], off offset:1024 nt
	global_load_dwordx4 v[212:215], v[186:187], off offset:2048 nt
	global_load_dwordx4 v[216:219], v[186:187], off offset:3072 nt
	global_load_dwordx4 v[220:223], v[104:105], off offset:-4096 nt
	global_load_dwordx4 v[224:227], v[104:105], off offset:-3072 nt
	global_load_dwordx4 v[228:231], v[104:105], off offset:-2048 nt
	global_load_dwordx4 v[232:235], v[104:105], off offset:-1024 nt
	global_load_dwordx4 v[236:239], v[104:105], off nt
	global_load_dwordx4 v[240:243], v[104:105], off offset:1024 nt
	global_load_dwordx4 v[244:247], v[104:105], off offset:2048 nt
	global_load_dwordx4 v[248:251], v[104:105], off offset:3072 nt
	s_movk_i32 s12, 0x1000
	s_mov_b32 s12, 0x880000
	s_mov_b32 s12, 0x881000
	s_mov_b32 s12, 0x1100000
	s_waitcnt vmcnt(15)
	v_pk_fma_f32 v[100:101], v[68:69], s[4:5], v[190:191] op_sel_hi:[1,0,1]
	v_pk_fma_f32 v[132:133], v[66:67], s[4:5], v[188:189] op_sel_hi:[1,0,1]
	global_load_dwordx4 v[188:191], v[106:107], off offset:-4096 nt
	s_waitcnt vmcnt(15)
	v_pk_fma_f32 v[134:135], v[72:73], s[4:5], v[194:195] op_sel_hi:[1,0,1]
	v_pk_fma_f32 v[136:137], v[70:71], s[4:5], v[192:193] op_sel_hi:[1,0,1]
	global_load_dwordx4 v[192:195], v[106:107], off offset:-3072 nt
	s_waitcnt vmcnt(15)
	v_pk_fma_f32 v[138:139], v[76:77], s[4:5], v[198:199] op_sel_hi:[1,0,1]
	v_pk_fma_f32 v[140:141], v[74:75], s[4:5], v[196:197] op_sel_hi:[1,0,1]
	global_load_dwordx4 v[196:199], v[106:107], off offset:-2048 nt
	s_waitcnt vmcnt(15)
	v_pk_fma_f32 v[142:143], v[80:81], s[4:5], v[202:203] op_sel_hi:[1,0,1]
	v_pk_fma_f32 v[144:145], v[78:79], s[4:5], v[200:201] op_sel_hi:[1,0,1]
	global_load_dwordx4 v[200:203], v[106:107], off offset:-1024 nt
	s_waitcnt vmcnt(15)
	v_pk_fma_f32 v[148:149], v[84:85], s[4:5], v[206:207] op_sel_hi:[1,0,1]
	v_pk_fma_f32 v[150:151], v[82:83], s[4:5], v[204:205] op_sel_hi:[1,0,1]
	global_load_dwordx4 v[204:207], v[106:107], off nt
	s_waitcnt vmcnt(15)
	v_pk_fma_f32 v[152:153], v[88:89], s[4:5], v[210:211] op_sel_hi:[1,0,1]
	v_pk_fma_f32 v[158:159], v[86:87], s[4:5], v[208:209] op_sel_hi:[1,0,1]
	global_load_dwordx4 v[208:211], v[106:107], off offset:1024 nt
	s_waitcnt vmcnt(15)
	v_pk_fma_f32 v[160:161], v[92:93], s[4:5], v[214:215] op_sel_hi:[1,0,1]
	v_pk_fma_f32 v[162:163], v[90:91], s[4:5], v[212:213] op_sel_hi:[1,0,1]
	global_load_dwordx4 v[212:215], v[106:107], off offset:2048 nt
	s_waitcnt vmcnt(15)
	v_pk_fma_f32 v[146:147], v[96:97], s[4:5], v[218:219] op_sel_hi:[1,0,1]
	v_pk_fma_f32 v[164:165], v[94:95], s[4:5], v[216:217] op_sel_hi:[1,0,1]
	global_load_dwordx4 v[216:219], v[106:107], off offset:3072 nt
	s_waitcnt vmcnt(15)
	v_pk_add_f32 v[132:133], v[132:133], v[220:221]
	v_pk_add_f32 v[100:101], v[100:101], v[222:223]
	global_load_dwordx4 v[220:223], v[108:109], off offset:-4096 nt
	s_waitcnt vmcnt(15)
	v_pk_add_f32 v[136:137], v[136:137], v[224:225]
	v_pk_add_f32 v[134:135], v[134:135], v[226:227]
	global_load_dwordx4 v[224:227], v[108:109], off offset:-3072 nt
	s_waitcnt vmcnt(15)
	v_pk_add_f32 v[140:141], v[140:141], v[228:229]
	v_pk_add_f32 v[138:139], v[138:139], v[230:231]
	global_load_dwordx4 v[228:231], v[108:109], off offset:-2048 nt
	s_mov_b32 s12, 0x1101000
	s_waitcnt vmcnt(15)
	v_pk_add_f32 v[144:145], v[144:145], v[232:233]
	v_pk_add_f32 v[142:143], v[142:143], v[234:235]
	global_load_dwordx4 v[232:235], v[108:109], off offset:-1024 nt
	s_waitcnt vmcnt(15)
	v_pk_add_f32 v[148:149], v[148:149], v[238:239]
	v_pk_add_f32 v[150:151], v[150:151], v[236:237]
	global_load_dwordx4 v[236:239], v[108:109], off nt
	s_waitcnt vmcnt(15)
	v_pk_add_f32 v[152:153], v[152:153], v[242:243]
	v_pk_add_f32 v[158:159], v[158:159], v[240:241]
	global_load_dwordx4 v[240:243], v[108:109], off offset:1024 nt
	s_waitcnt vmcnt(15)
	v_pk_add_f32 v[160:161], v[160:161], v[246:247]
	v_pk_add_f32 v[162:163], v[162:163], v[244:245]
	global_load_dwordx4 v[244:247], v[108:109], off offset:2048 nt
	s_mov_b32 s12, 0x1980000
	s_waitcnt vmcnt(15)
	v_pk_add_f32 v[146:147], v[146:147], v[250:251]
	v_pk_add_f32 v[164:165], v[164:165], v[248:249]
	global_load_dwordx4 v[248:251], v[108:109], off offset:3072 nt
	s_waitcnt vmcnt(15)
	v_pk_add_f32 v[170:171], v[100:101], v[190:191]
	v_pk_add_f32 v[132:133], v[132:133], v[188:189]
	s_waitcnt vmcnt(14)
	v_pk_add_f32 v[134:135], v[134:135], v[194:195]
	v_pk_add_f32 v[136:137], v[136:137], v[192:193]
	s_waitcnt vmcnt(13)
	v_pk_add_f32 v[138:139], v[138:139], v[198:199]
	v_pk_add_f32 v[140:141], v[140:141], v[196:197]
	s_waitcnt vmcnt(12)
	v_pk_add_f32 v[142:143], v[142:143], v[202:203]
	v_pk_add_f32 v[166:167], v[144:145], v[200:201]
	s_waitcnt vmcnt(11)
	v_pk_add_f32 v[180:181], v[148:149], v[206:207]
	v_pk_add_f32 v[182:183], v[150:151], v[204:205]
	s_waitcnt vmcnt(10)
	v_pk_add_f32 v[184:185], v[152:153], v[210:211]
	v_pk_add_f32 v[158:159], v[158:159], v[208:209]
	s_waitcnt vmcnt(9)
	v_pk_add_f32 v[160:161], v[160:161], v[214:215]
	v_pk_add_f32 v[162:163], v[162:163], v[212:213]
	s_waitcnt vmcnt(8)
	v_pk_add_f32 v[150:151], v[164:165], v[216:217]
	s_mov_b32 s12, 0x1981000
	v_pk_add_f32 v[148:149], v[146:147], v[218:219]
	s_waitcnt vmcnt(7)
	v_pk_add_f32 v[170:171], v[170:171], v[222:223]
	v_pk_add_f32 v[168:169], v[132:133], v[220:221]
	s_waitcnt vmcnt(6)
	v_pk_add_f32 v[144:145], v[134:135], v[226:227]
	v_pk_add_f32 v[146:147], v[136:137], v[224:225]
	s_waitcnt vmcnt(5)
	v_pk_add_f32 v[130:131], v[138:139], v[230:231]
	v_pk_add_f32 v[152:153], v[140:141], v[228:229]
	s_waitcnt vmcnt(4)
	v_pk_add_f32 v[128:129], v[142:143], v[234:235]
	v_pk_add_f32 v[134:135], v[166:167], v[232:233]
	v_mov_b32_e32 v167, v130
	v_mov_b32_e32 v166, v153
	v_mov_b32_e32 v130, v152
	v_mov_b32_e32 v152, v145
	v_mov_b32_e32 v153, v171
	v_mov_b32_e32 v145, v170
	s_waitcnt vmcnt(3)
	v_pk_add_f32 v[132:133], v[180:181], v[238:239]
	v_pk_add_f32 v[140:141], v[182:183], v[236:237]
	s_waitcnt vmcnt(2)
	v_pk_add_f32 v[138:139], v[184:185], v[242:243]
	v_pk_add_f32 v[158:159], v[158:159], v[240:241]
	s_waitcnt vmcnt(1)
	v_pk_add_f32 v[136:137], v[160:161], v[246:247]
	v_pk_add_f32 v[142:143], v[162:163], v[244:245]
	v_mov_b32_e32 v165, v138
	v_mov_b32_e32 v164, v159
	v_mov_b32_e32 v138, v158
	v_mov_b32_e32 v160, v133
	v_mov_b32_e32 v162, v141
	v_mov_b32_e32 v158, v147
	v_mov_b32_e32 v159, v169
	v_mov_b32_e32 v147, v168
	s_waitcnt vmcnt(0)
	v_pk_add_f32 v[100:101], v[148:149], v[250:251]
	v_pk_add_f32 v[98:99], v[150:151], v[248:249]
	v_mov_b32_e32 v148, v101
	v_mov_b32_e32 v150, v99
